# GDN scan waves at s_setprio 1 (same level as attention compute) instead of 3
# speedup vs baseline: 1.0033x; 1.0033x over previous
.LBB0_633:
	s_or_b64 exec, exec, s[36:37]
	v_readlane_b32 s36, v254, 0
	v_readlane_b32 s37, v254, 1
	s_mov_b32 s2, s82
	s_waitcnt lgkmcnt(0)
	s_barrier
	s_cmp_gt_i32 s2, 31
	s_cbranch_scc1 .LBB0_637
	s_setprio 1
	s_load_dwordx2 s[38:39], s[36:37], 0x98
	v_and_b32_e32 v100, 63, v218
	v_lshrrev_b32_e32 v101, 6, v218
	v_and_b32_e32 v102, 15, v100
	v_lshrrev_b32_e32 v103, 4, v100
	v_mul_u32_u24_e32 v104, 0x90, v102
	v_lshl_add_u32 v105, v103, 3, v104
	v_lshl_add_u32 v191, v101, 5, v105
	v_lshl_add_u32 v192, v103, 4, v104
	s_lshr_b32 s2, s82, 3
	s_lshl_b32 s3, s2, 12
	v_lshlrev_b32_e32 v105, 8, v102
	v_lshl_add_u32 v105, v101, 6, v105
	v_lshl_add_u32 v105, v103, 4, v105
	v_add_u32_e32 v186, s3, v105
	v_lshlrev_b32_e32 v105, 7, v102
	v_lshl_add_u32 v105, v101, 11, v105
	v_lshl_add_u32 v105, v103, 4, v105
	v_add_u32_e32 v187, 0x4000, v105
	v_add_u32_e32 v188, 0x6000, v105
	v_add_u32_e32 v189, 0x8000, v105
	v_add_u32_e32 v190, 0xa000, v105
	v_lshlrev_b32_e32 v105, 2, v102
	v_lshl_add_u32 v105, v103, 12, v105
	v_lshl_add_u32 v193, v101, 14, v105
	s_and_b32 s25, s82, 7
	s_lshr_b32 s26, s25, 2
	s_and_b32 s27, s25, 3
	s_waitcnt lgkmcnt(0)
	s_mul_i32 s28, s25, 0xc00000
	s_add_u32 s28, s28, 0x12000000
	s_add_u32 s40, s38, s28
	s_addc_u32 s41, s39, 0
	s_lshl_b32 s28, s25, 10
	s_add_u32 s28, s28, 0x1f500000
	s_add_u32 s42, s38, s28
	s_addc_u32 s43, s39, 0
	s_lshl_b32 s28, s26, 24
	s_lshl_b32 s29, s27, 8
	s_add_u32 s28, s28, s29
	s_lshl_b32 s29, s2, 6
	s_add_u32 s28, s28, s29
	s_add_u32 s28, s28, 0x18000000
	s_add_u32 s44, s38, s28
	s_addc_u32 s45, s39, 0
	s_mov_b32 s46, 0
	v_mov_b32_e32 v168, 0
	v_mov_b32_e32 v169, 0
	v_mov_b32_e32 v170, 0
	v_mov_b32_e32 v171, 0
	v_mov_b32_e32 v184, 0
	v_mov_b32_e32 v185, 0
	ds_write_b64 v191, v[184:185]
	global_load_dwordx4 v[0:3], v186, s[40:41]
	global_load_dwordx4 v[4:7], v187, s[40:41]
	global_load_dwordx4 v[8:11], v187, s[40:41] offset:64
	global_load_dwordx4 v[20:23], v189, s[40:41]
	global_load_dwordx4 v[24:27], v189, s[40:41] offset:64
	global_load_dwordx4 v[12:15], v188, s[40:41]
	global_load_dwordx4 v[16:19], v188, s[40:41] offset:64
	global_load_dwordx4 v[28:31], v190, s[40:41]
	global_load_dwordx4 v[32:35], v190, s[40:41] offset:64
	global_load_dword v36, v129, s[42:43]
	s_cmp_lt_u32 s46, 0xff
	s_cselect_b32 s2, 0xc000, 0
	s_cselect_b32 s3, 4, 0
	s_cselect_b32 s25, 1, 0
	s_add_u32 s40, s40, s2
	s_addc_u32 s41, s41, 0
	s_add_u32 s42, s42, s3
	s_addc_u32 s43, s43, 0
	s_add_u32 s46, s46, s25
	global_load_dwordx4 v[40:43], v186, s[40:41]
	global_load_dwordx4 v[44:47], v187, s[40:41]
	global_load_dwordx4 v[48:51], v187, s[40:41] offset:64
	global_load_dwordx4 v[60:63], v189, s[40:41]
	global_load_dwordx4 v[64:67], v189, s[40:41] offset:64
	global_load_dwordx4 v[52:55], v188, s[40:41]
	global_load_dwordx4 v[56:59], v188, s[40:41] offset:64
	global_load_dwordx4 v[68:71], v190, s[40:41]
	global_load_dwordx4 v[72:75], v190, s[40:41] offset:64
	global_load_dword v76, v129, s[42:43]
	s_cmp_lt_u32 s46, 0xff
	s_cselect_b32 s2, 0xc000, 0
	s_cselect_b32 s3, 4, 0
	s_cselect_b32 s25, 1, 0
	s_add_u32 s40, s40, s2
	s_addc_u32 s41, s41, 0
	s_add_u32 s42, s42, s3
	s_addc_u32 s43, s43, 0
	s_add_u32 s46, s46, s25
	global_load_dwordx4 v[80:83], v186, s[40:41]
	global_load_dwordx4 v[84:87], v187, s[40:41]
	global_load_dwordx4 v[88:91], v187, s[40:41] offset:64
	global_load_dwordx4 v[100:103], v189, s[40:41]
	global_load_dwordx4 v[104:107], v189, s[40:41] offset:64
	global_load_dwordx4 v[92:95], v188, s[40:41]
	global_load_dwordx4 v[96:99], v188, s[40:41] offset:64
	global_load_dwordx4 v[108:111], v190, s[40:41]
	global_load_dwordx4 v[112:115], v190, s[40:41] offset:64
	global_load_dword v116, v129, s[42:43]
	s_cmp_lt_u32 s46, 0xff
	s_cselect_b32 s2, 0xc000, 0
	s_cselect_b32 s3, 4, 0
	s_cselect_b32 s25, 1, 0
	s_add_u32 s40, s40, s2
	s_addc_u32 s41, s41, 0
	s_add_u32 s42, s42, s3
	s_addc_u32 s43, s43, 0
	s_add_u32 s46, s46, s25
	s_waitcnt lgkmcnt(0)
	s_barrier
	ds_read_b128 v[176:179], v192
	ds_read_b128 v[180:183], v192 offset:64
	global_load_dwordx4 v[130:133], v186, s[40:41]
	global_load_dwordx4 v[134:137], v187, s[40:41]
	global_load_dwordx4 v[138:141], v187, s[40:41] offset:64
	global_load_dwordx4 v[150:153], v189, s[40:41]
	global_load_dwordx4 v[154:157], v189, s[40:41] offset:64
	global_load_dwordx4 v[142:145], v188, s[40:41]
	global_load_dwordx4 v[146:149], v188, s[40:41] offset:64
	global_load_dwordx4 v[158:161], v190, s[40:41]
	global_load_dwordx4 v[162:165], v190, s[40:41] offset:64
	global_load_dword v166, v129, s[42:43]
	s_cmp_lt_u32 s46, 0xff
	s_cselect_b32 s2, 0xc000, 0
	s_cselect_b32 s3, 4, 0
	s_cselect_b32 s25, 1, 0
	s_add_u32 s40, s40, s2
	s_addc_u32 s41, s41, 0
	s_add_u32 s42, s42, s3
	s_addc_u32 s43, s43, 0
	s_add_u32 s46, s46, s25
	s_waitcnt vmcnt(30)
	v_mul_f32_e32 v168, v168, v36
	v_mul_f32_e32 v169, v169, v36
	v_mul_f32_e32 v170, v170, v36
	v_mul_f32_e32 v171, v171, v36
	s_waitcnt lgkmcnt(1)
	v_mfma_f32_16x16x32_bf16 v[0:3], v[4:7], v[176:179], v[0:3]
	s_waitcnt lgkmcnt(0)
	v_mfma_f32_16x16x32_bf16 v[0:3], v[8:11], v[180:183], v[0:3]
	v_mfma_f32_16x16x32_bf16 v[172:175], v[12:15], v[176:179], 0
	v_mfma_f32_16x16x32_bf16 v[172:175], v[16:19], v[180:183], v[172:175]
	s_nop 5
	v_cvt_pk_bf16_f32 v184, v0, v1
	v_cvt_pk_bf16_f32 v185, v2, v3
	ds_write_b64 v191, v[184:185] offset:2304
	s_waitcnt lgkmcnt(0)
	s_barrier
	ds_read_b128 v[176:179], v192 offset:2304
	ds_read_b128 v[180:183], v192 offset:2368
	s_waitcnt lgkmcnt(1)
	v_mfma_f32_16x16x32_bf16 v[168:171], v[20:23], v[176:179], v[168:171]
	s_waitcnt lgkmcnt(0)
	v_mfma_f32_16x16x32_bf16 v[168:171], v[24:27], v[180:183], v[168:171]
	v_mfma_f32_16x16x32_bf16 v[172:175], v[28:31], v[176:179], v[172:175]
	v_mfma_f32_16x16x32_bf16 v[172:175], v[32:35], v[180:183], v[172:175]
	s_nop 5
	v_cvt_pk_bf16_f32 v184, v168, v169
	v_cvt_pk_bf16_f32 v185, v170, v171
	ds_write_b64 v191, v[184:185]
	s_waitcnt lgkmcnt(0)
	s_barrier
	ds_read_b128 v[176:179], v192
	ds_read_b128 v[180:183], v192 offset:64
	global_store_dword v193, v172, s[44:45]
	global_store_dword v193, v173, s[44:45] offset:1024
	global_store_dword v193, v174, s[44:45] offset:2048
	global_store_dword v193, v175, s[44:45] offset:3072
	s_add_u32 s44, s44, 0x10000
	s_addc_u32 s45, s45, 0
	global_load_dwordx4 v[0:3], v186, s[40:41]
	global_load_dwordx4 v[4:7], v187, s[40:41]
	global_load_dwordx4 v[8:11], v187, s[40:41] offset:64
	global_load_dwordx4 v[20:23], v189, s[40:41]
	global_load_dwordx4 v[24:27], v189, s[40:41] offset:64
	global_load_dwordx4 v[12:15], v188, s[40:41]
	global_load_dwordx4 v[16:19], v188, s[40:41] offset:64
	global_load_dwordx4 v[28:31], v190, s[40:41]
	global_load_dwordx4 v[32:35], v190, s[40:41] offset:64
	global_load_dword v36, v129, s[42:43]
	s_cmp_lt_u32 s46, 0xff
	s_cselect_b32 s2, 0xc000, 0
	s_cselect_b32 s3, 4, 0
	s_cselect_b32 s25, 1, 0
	s_add_u32 s40, s40, s2
	s_addc_u32 s41, s41, 0
	s_add_u32 s42, s42, s3
	s_addc_u32 s43, s43, 0
	s_add_u32 s46, s46, s25
	s_waitcnt vmcnt(34)
	v_mul_f32_e32 v168, v168, v76
	v_mul_f32_e32 v169, v169, v76
	v_mul_f32_e32 v170, v170, v76
	v_mul_f32_e32 v171, v171, v76
	s_waitcnt lgkmcnt(1)
	v_mfma_f32_16x16x32_bf16 v[40:43], v[44:47], v[176:179], v[40:43]
	s_waitcnt lgkmcnt(0)
	v_mfma_f32_16x16x32_bf16 v[40:43], v[48:51], v[180:183], v[40:43]
	v_mfma_f32_16x16x32_bf16 v[172:175], v[52:55], v[176:179], 0
	v_mfma_f32_16x16x32_bf16 v[172:175], v[56:59], v[180:183], v[172:175]
	s_nop 5
	v_cvt_pk_bf16_f32 v184, v40, v41
	v_cvt_pk_bf16_f32 v185, v42, v43
	ds_write_b64 v191, v[184:185] offset:2304
	s_waitcnt lgkmcnt(0)
	s_barrier
	ds_read_b128 v[176:179], v192 offset:2304
	ds_read_b128 v[180:183], v192 offset:2368
	s_waitcnt lgkmcnt(1)
	v_mfma_f32_16x16x32_bf16 v[168:171], v[60:63], v[176:179], v[168:171]
	s_waitcnt lgkmcnt(0)
	v_mfma_f32_16x16x32_bf16 v[168:171], v[64:67], v[180:183], v[168:171]
	v_mfma_f32_16x16x32_bf16 v[172:175], v[68:71], v[176:179], v[172:175]
	v_mfma_f32_16x16x32_bf16 v[172:175], v[72:75], v[180:183], v[172:175]
	s_nop 5
	v_cvt_pk_bf16_f32 v184, v168, v169
	v_cvt_pk_bf16_f32 v185, v170, v171
	ds_write_b64 v191, v[184:185]
	s_waitcnt lgkmcnt(0)
	s_barrier
	ds_read_b128 v[176:179], v192
	ds_read_b128 v[180:183], v192 offset:64
	global_store_dword v193, v172, s[44:45]
	global_store_dword v193, v173, s[44:45] offset:1024
	global_store_dword v193, v174, s[44:45] offset:2048
	global_store_dword v193, v175, s[44:45] offset:3072
	s_add_u32 s44, s44, 0x10000
	s_addc_u32 s45, s45, 0
	global_load_dwordx4 v[40:43], v186, s[40:41]
	global_load_dwordx4 v[44:47], v187, s[40:41]
	global_load_dwordx4 v[48:51], v187, s[40:41] offset:64
	global_load_dwordx4 v[60:63], v189, s[40:41]
	global_load_dwordx4 v[64:67], v189, s[40:41] offset:64
	global_load_dwordx4 v[52:55], v188, s[40:41]
	global_load_dwordx4 v[56:59], v188, s[40:41] offset:64
	global_load_dwordx4 v[68:71], v190, s[40:41]
	global_load_dwordx4 v[72:75], v190, s[40:41] offset:64
	global_load_dword v76, v129, s[42:43]
	s_cmp_lt_u32 s46, 0xff
	s_cselect_b32 s2, 0xc000, 0
	s_cselect_b32 s3, 4, 0
	s_cselect_b32 s25, 1, 0
	s_add_u32 s40, s40, s2
	s_addc_u32 s41, s41, 0
	s_add_u32 s42, s42, s3
	s_addc_u32 s43, s43, 0
	s_add_u32 s46, s46, s25
	s_waitcnt vmcnt(38)
	v_mul_f32_e32 v168, v168, v116
	v_mul_f32_e32 v169, v169, v116
	v_mul_f32_e32 v170, v170, v116
	v_mul_f32_e32 v171, v171, v116
	s_waitcnt lgkmcnt(1)
	v_mfma_f32_16x16x32_bf16 v[80:83], v[84:87], v[176:179], v[80:83]
	s_waitcnt lgkmcnt(0)
	v_mfma_f32_16x16x32_bf16 v[80:83], v[88:91], v[180:183], v[80:83]
	v_mfma_f32_16x16x32_bf16 v[172:175], v[92:95], v[176:179], 0
	v_mfma_f32_16x16x32_bf16 v[172:175], v[96:99], v[180:183], v[172:175]
	s_nop 5
	v_cvt_pk_bf16_f32 v184, v80, v81
	v_cvt_pk_bf16_f32 v185, v82, v83
	ds_write_b64 v191, v[184:185] offset:2304
	s_waitcnt lgkmcnt(0)
	s_barrier
	ds_read_b128 v[176:179], v192 offset:2304
	ds_read_b128 v[180:183], v192 offset:2368
	s_waitcnt lgkmcnt(1)
	v_mfma_f32_16x16x32_bf16 v[168:171], v[100:103], v[176:179], v[168:171]
	s_waitcnt lgkmcnt(0)
	v_mfma_f32_16x16x32_bf16 v[168:171], v[104:107], v[180:183], v[168:171]
	v_mfma_f32_16x16x32_bf16 v[172:175], v[108:111], v[176:179], v[172:175]
	v_mfma_f32_16x16x32_bf16 v[172:175], v[112:115], v[180:183], v[172:175]
	s_nop 5
	v_cvt_pk_bf16_f32 v184, v168, v169
	v_cvt_pk_bf16_f32 v185, v170, v171
	ds_write_b64 v191, v[184:185]
	s_waitcnt lgkmcnt(0)
	s_barrier
	ds_read_b128 v[176:179], v192
	ds_read_b128 v[180:183], v192 offset:64
	global_store_dword v193, v172, s[44:45]
	global_store_dword v193, v173, s[44:45] offset:1024
	global_store_dword v193, v174, s[44:45] offset:2048
	global_store_dword v193, v175, s[44:45] offset:3072
	s_add_u32 s44, s44, 0x10000
	s_addc_u32 s45, s45, 0
	global_load_dwordx4 v[80:83], v186, s[40:41]
	global_load_dwordx4 v[84:87], v187, s[40:41]
	global_load_dwordx4 v[88:91], v187, s[40:41] offset:64
	global_load_dwordx4 v[100:103], v189, s[40:41]
	global_load_dwordx4 v[104:107], v189, s[40:41] offset:64
	global_load_dwordx4 v[92:95], v188, s[40:41]
	global_load_dwordx4 v[96:99], v188, s[40:41] offset:64
	global_load_dwordx4 v[108:111], v190, s[40:41]
	global_load_dwordx4 v[112:115], v190, s[40:41] offset:64
	global_load_dword v116, v129, s[42:43]
	s_cmp_lt_u32 s46, 0xff
	s_cselect_b32 s2, 0xc000, 0
	s_cselect_b32 s3, 4, 0
	s_cselect_b32 s25, 1, 0
	s_add_u32 s40, s40, s2
	s_addc_u32 s41, s41, 0
	s_add_u32 s42, s42, s3
	s_addc_u32 s43, s43, 0
	s_add_u32 s46, s46, s25
	s_waitcnt vmcnt(42)
	v_mul_f32_e32 v168, v168, v166
	v_mul_f32_e32 v169, v169, v166
	v_mul_f32_e32 v170, v170, v166
	v_mul_f32_e32 v171, v171, v166
	s_waitcnt lgkmcnt(1)
	v_mfma_f32_16x16x32_bf16 v[130:133], v[134:137], v[176:179], v[130:133]
	s_waitcnt lgkmcnt(0)
	v_mfma_f32_16x16x32_bf16 v[130:133], v[138:141], v[180:183], v[130:133]
	v_mfma_f32_16x16x32_bf16 v[172:175], v[142:145], v[176:179], 0
	v_mfma_f32_16x16x32_bf16 v[172:175], v[146:149], v[180:183], v[172:175]
	s_nop 5
	v_cvt_pk_bf16_f32 v184, v130, v131
	v_cvt_pk_bf16_f32 v185, v132, v133
	ds_write_b64 v191, v[184:185] offset:2304
	s_waitcnt lgkmcnt(0)
	s_barrier
	ds_read_b128 v[176:179], v192 offset:2304
	ds_read_b128 v[180:183], v192 offset:2368
	s_waitcnt lgkmcnt(1)
	v_mfma_f32_16x16x32_bf16 v[168:171], v[150:153], v[176:179], v[168:171]
	s_waitcnt lgkmcnt(0)
	v_mfma_f32_16x16x32_bf16 v[168:171], v[154:157], v[180:183], v[168:171]
	v_mfma_f32_16x16x32_bf16 v[172:175], v[158:161], v[176:179], v[172:175]
	v_mfma_f32_16x16x32_bf16 v[172:175], v[162:165], v[180:183], v[172:175]
	s_nop 5
	v_cvt_pk_bf16_f32 v184, v168, v169
	v_cvt_pk_bf16_f32 v185, v170, v171
	ds_write_b64 v191, v[184:185]
	s_waitcnt lgkmcnt(0)
	s_barrier
	s_mov_b32 s47, 63
